# input projection: half of the weight-converting workgroups convert before their tiles instead of after (de-phases epilogue store bursts)
# baseline (speedup 1.0000x reference)
; #define LAS __attribute__((address_space(3)))
; #define otid() ((wv << 6) | olane())
; __device__ __forceinline__ void convert_weights(LAS unsigned char* lds, KP p, int l, int wv) {
;     unsigned char* ws = p->ws;
;     const int tid_ = otid(); const int lane = tid_ & 63, wid = tid_ >> 6;
;     LAS float* scr = (LAS float*)(lds + wid * 8704);
;     const int gw = blockIdx.x * 8 + wid, NGW = gridDim.x * 8;
;     constexpr int I_IN = 16 * (DIN / 32), I_UQ = 6 * 24, I_UKV = 4 * 32, I_BR = 8 * 32, I_O = 16 * 32, I_F1 = 16 * 128, I_F2 = 64 * 32;
;     constexpr int NIT = I_IN + I_UQ + I_UKV + 3 * I_BR + I_O + I_F1 + I_F2;
;     const int BIG = 1 << 30;
;     for (int it = gw; it < NIT; it += NGW) {
;         int r = it;
;         if (r < I_IN) { tr_item(p->w_in + (size_t)l * DM * DIN, DIN, (bf16_t*)(ws + WS_WIN), DM, 0, NGATE0, NPM - NGATE0, 1, 0, scr, r, lane); continue; } r -= I_IN;
;         if (r < I_UQ) { const int nb = r % 24, hh = nb / 3, part = nb % 3, dest = part < 2 ? (2 * hh + part) * 32 : 512 + 32 * hh;
;             tr_item(p->w_uq + (size_t)l * 384 * 768, 768, (bf16_t*)(ws + WS_WUQ), 384, dest - 32 * nb, BIG, 0, 1, 0, scr, r, lane); continue; } r -= I_UQ;
;         if (r < I_UKV) { tr_item(p->w_ukv + (size_t)l * 256 * 1024, 1024, (bf16_t*)(ws + WS_WUKV), 256, 0, BIG, 0, 1, 0, scr, r, lane); continue; } r -= I_UKV;
;         if (r < 3 * I_BR) { const int z3 = r / I_BR, z = z3 == 2 ? 3 : z3; tr_item(p->w_branch + ((size_t)l * 4 + z) * 512 * 1024, 1024, (bf16_t*)(ws + WS_WBR), 512, z * 1024, BIG, 0, 1, 0, scr, r % I_BR, lane); continue; } r -= 3 * I_BR;
;         if (r < I_O) { tr_item(p->w_o + (size_t)l * DM * DM, DM, (bf16_t*)(ws + WS_WO4), 4096, 0, BIG, 0, 1, 0, scr, r, lane); continue; } r -= I_O;
;         if (r < I_F1) { tr_item(p->w_ff1 + (size_t)l * DM * DFF, DFF, (bf16_t*)(ws + WS_WF1), DM, 0, BIG, 0, 1, 0, scr, r, lane); continue; } r -= I_F1;
;         tr_item(p->w_ff2 + (size_t)l * DFF * DM, DM, (bf16_t*)(ws + WS_WF2), DFF, 0, BIG, 0, 1, 0, scr, r, lane);
;     }
.Lp1_entry:
	s_mov_b32 s0, 0
	s_cmp_lt_u32 s79, 0x48
	s_cbranch_scc1 .Lp1_flag
	s_bitcmp1_b32 s79, 3
	s_cselect_b32 s0, 1, 0
.Lp1_flag:
	s_nop 0
	v_writelane_b32 v255, s0, 60
	s_cmp_eq_u32 s0, 1
	s_cbranch_scc1 .Lp0b_body

; #define LAS __attribute__((address_space(3)))
; #define otid() ((wv << 6) | olane())
; __device__ __forceinline__ void convert_weights(LAS unsigned char* lds, KP p, int l, int wv) {
;     unsigned char* ws = p->ws;
;     const int tid_ = otid(); const int lane = tid_ & 63, wid = tid_ >> 6;
;     LAS float* scr = (LAS float*)(lds + wid * 8704);
;     const int gw = blockIdx.x * 8 + wid, NGW = gridDim.x * 8;
;     constexpr int I_IN = 16 * (DIN / 32), I_UQ = 6 * 24, I_UKV = 4 * 32, I_BR = 8 * 32, I_O = 16 * 32, I_F1 = 16 * 128, I_F2 = 64 * 32;
;     constexpr int NIT = I_IN + I_UQ + I_UKV + 3 * I_BR + I_O + I_F1 + I_F2;
;     const int BIG = 1 << 30;
;     for (int it = gw; it < NIT; it += NGW) {
;         int r = it;
;         if (r < I_IN) { tr_item(p->w_in + (size_t)l * DM * DIN, DIN, (bf16_t*)(ws + WS_WIN), DM, 0, NGATE0, NPM - NGATE0, 1, 0, scr, r, lane); continue; } r -= I_IN;
;         if (r < I_UQ) { const int nb = r % 24, hh = nb / 3, part = nb % 3, dest = part < 2 ? (2 * hh + part) * 32 : 512 + 32 * hh;
;             tr_item(p->w_uq + (size_t)l * 384 * 768, 768, (bf16_t*)(ws + WS_WUQ), 384, dest - 32 * nb, BIG, 0, 1, 0, scr, r, lane); continue; } r -= I_UQ;
;         if (r < I_UKV) { tr_item(p->w_ukv + (size_t)l * 256 * 1024, 1024, (bf16_t*)(ws + WS_WUKV), 256, 0, BIG, 0, 1, 0, scr, r, lane); continue; } r -= I_UKV;
;         if (r < 3 * I_BR) { const int z3 = r / I_BR, z = z3 == 2 ? 3 : z3; tr_item(p->w_branch + ((size_t)l * 4 + z) * 512 * 1024, 1024, (bf16_t*)(ws + WS_WBR), 512, z * 1024, BIG, 0, 1, 0, scr, r % I_BR, lane); continue; } r -= 3 * I_BR;
;         if (r < I_O) { tr_item(p->w_o + (size_t)l * DM * DM, DM, (bf16_t*)(ws + WS_WO4), 4096, 0, BIG, 0, 1, 0, scr, r, lane); continue; } r -= I_O;
;         if (r < I_F1) { tr_item(p->w_ff1 + (size_t)l * DM * DFF, DFF, (bf16_t*)(ws + WS_WF1), DM, 0, BIG, 0, 1, 0, scr, r, lane); continue; } r -= I_F1;
;         tr_item(p->w_ff2 + (size_t)l * DFF * DM, DM, (bf16_t*)(ws + WS_WF2), DFF, 0, BIG, 0, 1, 0, scr, r, lane);
;     }
.LBB0_317:
	s_cmp_lt_u32 s79, 0x48
	s_cbranch_scc1 .Lp0b_skip
	s_bitcmp1_b32 s79, 3
	s_cbranch_scc1 .Lp0b_skip
.Lp0b_body:
	v_readlane_b32 s0, v255, 6
	v_readlane_b32 s1, v255, 7
	v_readlane_b32 s2, v255, 23
	v_readlane_b32 s3, v255, 24
	v_readlane_b32 s4, v255, 25
	v_readlane_b32 s5, v255, 26
	v_readlane_b32 s6, v255, 29
	v_readlane_b32 s7, v255, 30
	s_nop 3
	v_writelane_b32 v255, s60, 49
	v_writelane_b32 v255, s66, 50
	v_writelane_b32 v255, s0, 51
	v_writelane_b32 v255, s1, 52
	v_writelane_b32 v255, s2, 53
	v_writelane_b32 v255, s3, 54
	v_writelane_b32 v255, s4, 55
	v_writelane_b32 v255, s5, 56
	v_writelane_b32 v255, s6, 57
	v_writelane_b32 v255, s7, 58
	s_sub_i32 s79, s79, 0x48
	s_movk_i32 s60, 0xb8
	s_mov_b32 s66, 0x17000
	s_movk_i32 s89, 0x47ff
	s_lshl_b32 s0, s79, 3
	s_lshl_b32 s1, s79, 9
	s_mov_b32 s2, 0x170000
	s_mov_b32 s3, 0
	s_mov_b32 s4, 0x5c0000
	s_movk_i32 s6, 0x5c0
	v_writelane_b32 v255, s0, 6
	v_writelane_b32 v255, s1, 7
	v_writelane_b32 v255, s2, 23
	v_writelane_b32 v255, s3, 24
	v_writelane_b32 v255, s4, 25
	v_writelane_b32 v255, s3, 26
	v_writelane_b32 v255, s6, 29
	v_writelane_b32 v255, s3, 30

; __device__ __forceinline__ void convert_weights(LAS unsigned char* lds, KP p, int l, int wv) {
;     ...
;     for (int it = gw; it < NIT; it += NGW) {
;         int r = it;
;         if (r < I_IN) { tr_item(p->w_in + (size_t)l * DM * DIN, DIN, (bf16_t*)(ws + WS_WIN), DM, 0, NGATE0, NPM - NGATE0, 1, 0, scr, r, lane); continue; } r -= I_IN;
;         if (r < I_UQ) { const int nb = r % 24, hh = nb / 3, part = nb % 3, dest = part < 2 ? (2 * hh + part) * 32 : 512 + 32 * hh;
;             tr_item(p->w_uq + (size_t)l * 384 * 768, 768, (bf16_t*)(ws + WS_WUQ), 384, dest - 32 * nb, BIG, 0, 1, 0, scr, r, lane); continue; } r -= I_UQ;
;         if (r < I_UKV) { tr_item(p->w_ukv + (size_t)l * 256 * 1024, 1024, (bf16_t*)(ws + WS_WUKV), 256, 0, BIG, 0, 1, 0, scr, r, lane); continue; } r -= I_UKV;
;         if (r < 3 * I_BR) { const int z3 = r / I_BR, z = z3 == 2 ? 3 : z3; tr_item(p->w_branch + ((size_t)l * 4 + z) * 512 * 1024, 1024, (bf16_t*)(ws + WS_WBR), 512, z * 1024, BIG, 0, 1, 0, scr, r % I_BR, lane); continue; } r -= 3 * I_BR;
;         if (r < I_O) { tr_item(p->w_o + (size_t)l * DM * DM, DM, (bf16_t*)(ws + WS_WO4), 4096, 0, BIG, 0, 1, 0, scr, r, lane); continue; } r -= I_O;
;         if (r < I_F1) { tr_item(p->w_ff1 + (size_t)l * DM * DFF, DFF, (bf16_t*)(ws + WS_WF1), DM, 0, BIG, 0, 1, 0, scr, r, lane); continue; } r -= I_F1;
;         tr_item(p->w_ff2 + (size_t)l * DFF * DM, DM, (bf16_t*)(ws + WS_WF2), DFF, 0, BIG, 0, 1, 0, scr, r, lane);
;     }
.Lb_exit:
	v_readlane_b32 s79, v255, 37
	v_readlane_b32 s60, v255, 49
	v_readlane_b32 s66, v255, 50
	v_readlane_b32 s0, v255, 51
	v_readlane_b32 s1, v255, 52
	v_readlane_b32 s2, v255, 53
	v_readlane_b32 s3, v255, 54
	v_readlane_b32 s4, v255, 55
	v_readlane_b32 s5, v255, 56
	v_readlane_b32 s6, v255, 57
	v_readlane_b32 s7, v255, 58
	s_movk_i32 s89, 0x900
	s_nop 3
	v_writelane_b32 v255, s0, 6
	v_writelane_b32 v255, s1, 7
	v_writelane_b32 v255, s2, 23
	v_writelane_b32 v255, s3, 24
	v_writelane_b32 v255, s4, 25
	v_writelane_b32 v255, s5, 26
	v_writelane_b32 v255, s6, 29
	v_writelane_b32 v255, s7, 30
	v_readlane_b32 s0, v255, 60
	s_nop 3
	s_cmp_eq_u32 s0, 1
	s_cbranch_scc0 .Lp0b_skip
	s_mov_b32 s0, 0
	s_nop 0
	v_writelane_b32 v255, s0, 60
	s_waitcnt vmcnt(0) lgkmcnt(0)
	s_branch .Lp1_go
